# P0: batched w_ada/c loads in mod unit and hand-written column-max unit (32 loads in flight instead of serialized round trips)
# speedup vs baseline: 1.0667x; 1.0329x over previous
.LBB0_38:
	s_andn2_b64 vcc, exec, s[0:1]
	s_cbranch_vccnz .LBB0_140
	s_lshl_b32 s0, s47, 6
	s_and_b32 s0, s0, 0x3f00
	v_readlane_b32 s8, v247, 23
	v_readlane_b32 s9, v247, 24
	v_add_u32_e32 v52, s0, v107
	s_lshl_b32 s0, s47, 8
	s_and_b32 s0, s0, 0x300
	s_mulk_i32 s0, 0x7800
	v_mov_b32_e32 v53, 0
	s_add_u32 s0, s8, s0
	s_addc_u32 s1, s9, 0
	s_mov_b64 s[2:3], 0x7800
	v_mov_b32_e32 v21, 0
	s_mov_b32 s4, 0
	v_lshl_add_u64 v[54:55], v[52:53], 2, s[0:1]
.Lp0_cmax:
	global_load_dword v112, v[54:55], off
	v_lshl_add_u64 v[54:55], v[54:55], 0, s[2:3]
	global_load_dword v113, v[54:55], off
	v_lshl_add_u64 v[54:55], v[54:55], 0, s[2:3]
	global_load_dword v114, v[54:55], off
	v_lshl_add_u64 v[54:55], v[54:55], 0, s[2:3]
	global_load_dword v115, v[54:55], off
	v_lshl_add_u64 v[54:55], v[54:55], 0, s[2:3]
	global_load_dword v116, v[54:55], off
	v_lshl_add_u64 v[54:55], v[54:55], 0, s[2:3]
	global_load_dword v117, v[54:55], off
	v_lshl_add_u64 v[54:55], v[54:55], 0, s[2:3]
	global_load_dword v118, v[54:55], off
	v_lshl_add_u64 v[54:55], v[54:55], 0, s[2:3]
	global_load_dword v119, v[54:55], off
	v_lshl_add_u64 v[54:55], v[54:55], 0, s[2:3]
	global_load_dword v120, v[54:55], off
	v_lshl_add_u64 v[54:55], v[54:55], 0, s[2:3]
	global_load_dword v121, v[54:55], off
	v_lshl_add_u64 v[54:55], v[54:55], 0, s[2:3]
	global_load_dword v122, v[54:55], off
	v_lshl_add_u64 v[54:55], v[54:55], 0, s[2:3]
	global_load_dword v123, v[54:55], off
	v_lshl_add_u64 v[54:55], v[54:55], 0, s[2:3]
	global_load_dword v124, v[54:55], off
	v_lshl_add_u64 v[54:55], v[54:55], 0, s[2:3]
	global_load_dword v125, v[54:55], off
	v_lshl_add_u64 v[54:55], v[54:55], 0, s[2:3]
	global_load_dword v126, v[54:55], off
	v_lshl_add_u64 v[54:55], v[54:55], 0, s[2:3]
	global_load_dword v127, v[54:55], off
	v_lshl_add_u64 v[54:55], v[54:55], 0, s[2:3]
	global_load_dword v158, v[54:55], off
	v_lshl_add_u64 v[54:55], v[54:55], 0, s[2:3]
	global_load_dword v159, v[54:55], off
	v_lshl_add_u64 v[54:55], v[54:55], 0, s[2:3]
	global_load_dword v160, v[54:55], off
	v_lshl_add_u64 v[54:55], v[54:55], 0, s[2:3]
	global_load_dword v161, v[54:55], off
	v_lshl_add_u64 v[54:55], v[54:55], 0, s[2:3]
	global_load_dword v162, v[54:55], off
	v_lshl_add_u64 v[54:55], v[54:55], 0, s[2:3]
	global_load_dword v163, v[54:55], off
	v_lshl_add_u64 v[54:55], v[54:55], 0, s[2:3]
	global_load_dword v164, v[54:55], off
	v_lshl_add_u64 v[54:55], v[54:55], 0, s[2:3]
	global_load_dword v165, v[54:55], off
	v_lshl_add_u64 v[54:55], v[54:55], 0, s[2:3]
	global_load_dword v166, v[54:55], off
	v_lshl_add_u64 v[54:55], v[54:55], 0, s[2:3]
	global_load_dword v167, v[54:55], off
	v_lshl_add_u64 v[54:55], v[54:55], 0, s[2:3]
	global_load_dword v168, v[54:55], off
	v_lshl_add_u64 v[54:55], v[54:55], 0, s[2:3]
	global_load_dword v169, v[54:55], off
	v_lshl_add_u64 v[54:55], v[54:55], 0, s[2:3]
	global_load_dword v170, v[54:55], off
	v_lshl_add_u64 v[54:55], v[54:55], 0, s[2:3]
	global_load_dword v171, v[54:55], off
	v_lshl_add_u64 v[54:55], v[54:55], 0, s[2:3]
	global_load_dword v172, v[54:55], off
	v_lshl_add_u64 v[54:55], v[54:55], 0, s[2:3]
	global_load_dword v173, v[54:55], off
	v_lshl_add_u64 v[54:55], v[54:55], 0, s[2:3]
	s_waitcnt vmcnt(30)
	v_max3_f32 v21, v21, |v112|, |v113|
	s_waitcnt vmcnt(28)
	v_max3_f32 v21, v21, |v114|, |v115|
	s_waitcnt vmcnt(26)
	v_max3_f32 v21, v21, |v116|, |v117|
	s_waitcnt vmcnt(24)
	v_max3_f32 v21, v21, |v118|, |v119|
	s_waitcnt vmcnt(22)
	v_max3_f32 v21, v21, |v120|, |v121|
	s_waitcnt vmcnt(20)
	v_max3_f32 v21, v21, |v122|, |v123|
	s_waitcnt vmcnt(18)
	v_max3_f32 v21, v21, |v124|, |v125|
	s_waitcnt vmcnt(16)
	v_max3_f32 v21, v21, |v126|, |v127|
	s_waitcnt vmcnt(14)
	v_max3_f32 v21, v21, |v158|, |v159|
	s_waitcnt vmcnt(12)
	v_max3_f32 v21, v21, |v160|, |v161|
	s_waitcnt vmcnt(10)
	v_max3_f32 v21, v21, |v162|, |v163|
	s_waitcnt vmcnt(8)
	v_max3_f32 v21, v21, |v164|, |v165|
	s_waitcnt vmcnt(6)
	v_max3_f32 v21, v21, |v166|, |v167|
	s_waitcnt vmcnt(4)
	v_max3_f32 v21, v21, |v168|, |v169|
	s_waitcnt vmcnt(2)
	v_max3_f32 v21, v21, |v170|, |v171|
	s_waitcnt vmcnt(0)
	v_max3_f32 v21, v21, |v172|, |v173|
	s_add_i32 s4, s4, 1
	s_cmp_eq_u32 s4, 8
	s_cbranch_scc0 .Lp0_cmax
	v_readlane_b32 s6, v248, 26
	v_readlane_b32 s7, v248, 27
	s_nop 1
	v_lshl_add_u64 v[52:53], v[52:53], 2, s[6:7]
	global_atomic_smax v[52:53], v21, off

.LBB0_143:
	v_lshlrev_b32_e32 v35, 6, v130
	s_mov_b32 s2, 0
.Lp0_silu:
	s_mov_b64 s[6:7], 0x1000
	v_lshl_add_u64 v[54:55], v[52:53], 0, s[6:7]
	global_load_dword v142, v[52:53], off
	global_load_dword v143, v[52:53], off offset:1024
	global_load_dword v144, v[52:53], off offset:2048
	global_load_dword v145, v[52:53], off offset:3072
	global_load_dword v146, v[54:55], off
	global_load_dword v147, v[54:55], off offset:1024
	global_load_dword v148, v[54:55], off offset:2048
	global_load_dword v149, v[54:55], off offset:3072
	s_mov_b64 s[6:7], 0x2000
	v_lshl_add_u64 v[52:53], v[52:53], 0, s[6:7]
	s_waitcnt vmcnt(7)
	v_mul_f32_e32 v23, 0xbfb8aa3b, v142
	v_exp_f32_e32 v23, v23
	s_nop 0
	v_add_f32_e32 v23, 1.0, v23
	v_div_scale_f32 v25, s[6:7], v23, v23, v142
	v_rcp_f32_e32 v27, v25
	s_nop 0
	v_fma_f32 v29, -v25, v27, 1.0
	v_fmac_f32_e32 v27, v29, v27
	v_div_scale_f32 v29, vcc, v142, v23, v142
	v_mul_f32_e32 v31, v29, v27
	v_fma_f32 v33, -v25, v31, v29
	v_fmac_f32_e32 v31, v33, v27
	v_fma_f32 v25, -v25, v31, v29
	v_div_fmas_f32 v25, v25, v27, v31
	v_div_fixup_f32 v21, v25, v23, v142
	ds_write_b32 v35, v21
	s_waitcnt vmcnt(6)
	v_mul_f32_e32 v23, 0xbfb8aa3b, v143
	v_exp_f32_e32 v23, v23
	s_nop 0
	v_add_f32_e32 v23, 1.0, v23
	v_div_scale_f32 v25, s[6:7], v23, v23, v143
	v_rcp_f32_e32 v27, v25
	s_nop 0
	v_fma_f32 v29, -v25, v27, 1.0
	v_fmac_f32_e32 v27, v29, v27
	v_div_scale_f32 v29, vcc, v143, v23, v143
	v_mul_f32_e32 v31, v29, v27
	v_fma_f32 v33, -v25, v31, v29
	v_fmac_f32_e32 v31, v33, v27
	v_fma_f32 v25, -v25, v31, v29
	v_div_fmas_f32 v25, v25, v27, v31
	v_div_fixup_f32 v21, v25, v23, v143
	ds_write_b32 v35, v21 offset:16384
	s_waitcnt vmcnt(5)
	v_mul_f32_e32 v23, 0xbfb8aa3b, v144
	v_exp_f32_e32 v23, v23
	s_nop 0
	v_add_f32_e32 v23, 1.0, v23
	v_div_scale_f32 v25, s[6:7], v23, v23, v144
	v_rcp_f32_e32 v27, v25
	s_nop 0
	v_fma_f32 v29, -v25, v27, 1.0
	v_fmac_f32_e32 v27, v29, v27
	v_div_scale_f32 v29, vcc, v144, v23, v144
	v_mul_f32_e32 v31, v29, v27
	v_fma_f32 v33, -v25, v31, v29
	v_fmac_f32_e32 v31, v33, v27
	v_fma_f32 v25, -v25, v31, v29
	v_div_fmas_f32 v25, v25, v27, v31
	v_div_fixup_f32 v21, v25, v23, v144
	ds_write_b32 v35, v21 offset:32768
	s_waitcnt vmcnt(4)
	v_mul_f32_e32 v23, 0xbfb8aa3b, v145
	v_exp_f32_e32 v23, v23
	s_nop 0
	v_add_f32_e32 v23, 1.0, v23
	v_div_scale_f32 v25, s[6:7], v23, v23, v145
	v_rcp_f32_e32 v27, v25
	s_nop 0
	v_fma_f32 v29, -v25, v27, 1.0
	v_fmac_f32_e32 v27, v29, v27
	v_div_scale_f32 v29, vcc, v145, v23, v145
	v_mul_f32_e32 v31, v29, v27
	v_fma_f32 v33, -v25, v31, v29
	v_fmac_f32_e32 v31, v33, v27
	v_fma_f32 v25, -v25, v31, v29
	v_div_fmas_f32 v25, v25, v27, v31
	v_div_fixup_f32 v21, v25, v23, v145
	ds_write_b32 v35, v21 offset:49152
	s_waitcnt vmcnt(3)
	v_mul_f32_e32 v23, 0xbfb8aa3b, v146
	v_exp_f32_e32 v23, v23
	s_nop 0
	v_add_f32_e32 v23, 1.0, v23
	v_div_scale_f32 v25, s[6:7], v23, v23, v146
	v_rcp_f32_e32 v27, v25
	s_nop 0
	v_fma_f32 v29, -v25, v27, 1.0
	v_fmac_f32_e32 v27, v29, v27
	v_div_scale_f32 v29, vcc, v146, v23, v146
	v_mul_f32_e32 v31, v29, v27
	v_fma_f32 v33, -v25, v31, v29
	v_fmac_f32_e32 v31, v33, v27
	v_fma_f32 v25, -v25, v31, v29
	v_div_fmas_f32 v25, v25, v27, v31
	v_div_fixup_f32 v21, v25, v23, v146
	ds_write_b32 v35, v21 offset:4
	s_waitcnt vmcnt(2)
	v_mul_f32_e32 v23, 0xbfb8aa3b, v147
	v_exp_f32_e32 v23, v23
	s_nop 0
	v_add_f32_e32 v23, 1.0, v23
	v_div_scale_f32 v25, s[6:7], v23, v23, v147
	v_rcp_f32_e32 v27, v25
	s_nop 0
	v_fma_f32 v29, -v25, v27, 1.0
	v_fmac_f32_e32 v27, v29, v27
	v_div_scale_f32 v29, vcc, v147, v23, v147
	v_mul_f32_e32 v31, v29, v27
	v_fma_f32 v33, -v25, v31, v29
	v_fmac_f32_e32 v31, v33, v27
	v_fma_f32 v25, -v25, v31, v29
	v_div_fmas_f32 v25, v25, v27, v31
	v_div_fixup_f32 v21, v25, v23, v147
	ds_write_b32 v35, v21 offset:16388
	s_waitcnt vmcnt(1)
	v_mul_f32_e32 v23, 0xbfb8aa3b, v148
	v_exp_f32_e32 v23, v23
	s_nop 0
	v_add_f32_e32 v23, 1.0, v23
	v_div_scale_f32 v25, s[6:7], v23, v23, v148
	v_rcp_f32_e32 v27, v25
	s_nop 0
	v_fma_f32 v29, -v25, v27, 1.0
	v_fmac_f32_e32 v27, v29, v27
	v_div_scale_f32 v29, vcc, v148, v23, v148
	v_mul_f32_e32 v31, v29, v27
	v_fma_f32 v33, -v25, v31, v29
	v_fmac_f32_e32 v31, v33, v27
	v_fma_f32 v25, -v25, v31, v29
	v_div_fmas_f32 v25, v25, v27, v31
	v_div_fixup_f32 v21, v25, v23, v148
	ds_write_b32 v35, v21 offset:32772
	s_waitcnt vmcnt(0)
	v_mul_f32_e32 v23, 0xbfb8aa3b, v149
	v_exp_f32_e32 v23, v23
	s_nop 0
	v_add_f32_e32 v23, 1.0, v23
	v_div_scale_f32 v25, s[6:7], v23, v23, v149
	v_rcp_f32_e32 v27, v25
	s_nop 0
	v_fma_f32 v29, -v25, v27, 1.0
	v_fmac_f32_e32 v27, v29, v27
	v_div_scale_f32 v29, vcc, v149, v23, v149
	v_mul_f32_e32 v31, v29, v27
	v_fma_f32 v33, -v25, v31, v29
	v_fmac_f32_e32 v31, v33, v27
	v_fma_f32 v25, -v25, v31, v29
	v_div_fmas_f32 v25, v25, v27, v31
	v_div_fixup_f32 v21, v25, v23, v149
	ds_write_b32 v35, v21 offset:49156
	v_add_u32_e32 v35, 8, v35
	s_add_i32 s2, s2, 1
	s_cmp_eq_u32 s2, 8
	s_cbranch_scc0 .Lp0_silu
	v_ashrrev_i32_e32 v19, 31, v18
	v_mov_b32_e32 v64, 0
	v_lshl_add_u64 v[52:53], v[18:19], 2, v[16:17]
	s_mov_b64 s[4:5], 0
	v_mov_b32_e32 v0, v109
	v_mov_b32_e32 v65, v64
	v_mov_b32_e32 v56, v64
	v_mov_b32_e32 v57, v64
	v_mov_b32_e32 v58, v64
	v_mov_b32_e32 v59, v64
	v_mov_b32_e32 v60, v64
	v_mov_b32_e32 v61, v64
	v_mov_b32_e32 v62, v64
	v_mov_b32_e32 v63, v64
	v_mov_b32_e32 v66, v64
	v_mov_b32_e32 v67, v64
	v_mov_b32_e32 v68, v64
	v_mov_b32_e32 v69, v64
	v_mov_b32_e32 v70, v64
	v_mov_b32_e32 v71, v64
	s_waitcnt lgkmcnt(0)
	s_barrier
.LBB0_145:
	s_mov_b64 s[2:3], 0x6000
	v_lshl_add_u64 v[54:55], v[52:53], 0, s[4:5]
	global_load_dword v112, v[54:55], off
	v_lshl_add_u64 v[54:55], v[54:55], 0, s[2:3]
	global_load_dword v113, v[54:55], off
	v_lshl_add_u64 v[54:55], v[54:55], 0, s[2:3]
	global_load_dword v114, v[54:55], off
	v_lshl_add_u64 v[54:55], v[54:55], 0, s[2:3]
	global_load_dword v115, v[54:55], off
	v_lshl_add_u64 v[54:55], v[54:55], 0, s[2:3]
	global_load_dword v116, v[54:55], off
	v_lshl_add_u64 v[54:55], v[54:55], 0, s[2:3]
	global_load_dword v117, v[54:55], off
	v_lshl_add_u64 v[54:55], v[54:55], 0, s[2:3]
	global_load_dword v118, v[54:55], off
	v_lshl_add_u64 v[54:55], v[54:55], 0, s[2:3]
	global_load_dword v119, v[54:55], off
	v_lshl_add_u64 v[54:55], v[54:55], 0, s[2:3]
	global_load_dword v120, v[54:55], off
	v_lshl_add_u64 v[54:55], v[54:55], 0, s[2:3]
	global_load_dword v121, v[54:55], off
	v_lshl_add_u64 v[54:55], v[54:55], 0, s[2:3]
	global_load_dword v122, v[54:55], off
	v_lshl_add_u64 v[54:55], v[54:55], 0, s[2:3]
	global_load_dword v123, v[54:55], off
	v_lshl_add_u64 v[54:55], v[54:55], 0, s[2:3]
	global_load_dword v124, v[54:55], off
	v_lshl_add_u64 v[54:55], v[54:55], 0, s[2:3]
	global_load_dword v125, v[54:55], off
	v_lshl_add_u64 v[54:55], v[54:55], 0, s[2:3]
	global_load_dword v126, v[54:55], off
	v_lshl_add_u64 v[54:55], v[54:55], 0, s[2:3]
	global_load_dword v127, v[54:55], off
	v_lshl_add_u64 v[54:55], v[54:55], 0, s[2:3]
	global_load_dword v158, v[54:55], off
	v_lshl_add_u64 v[54:55], v[54:55], 0, s[2:3]
	global_load_dword v159, v[54:55], off
	v_lshl_add_u64 v[54:55], v[54:55], 0, s[2:3]
	global_load_dword v160, v[54:55], off
	v_lshl_add_u64 v[54:55], v[54:55], 0, s[2:3]
	global_load_dword v161, v[54:55], off
	v_lshl_add_u64 v[54:55], v[54:55], 0, s[2:3]
	global_load_dword v162, v[54:55], off
	v_lshl_add_u64 v[54:55], v[54:55], 0, s[2:3]
	global_load_dword v163, v[54:55], off
	v_lshl_add_u64 v[54:55], v[54:55], 0, s[2:3]
	global_load_dword v164, v[54:55], off
	v_lshl_add_u64 v[54:55], v[54:55], 0, s[2:3]
	global_load_dword v165, v[54:55], off
	v_lshl_add_u64 v[54:55], v[54:55], 0, s[2:3]
	global_load_dword v166, v[54:55], off
	v_lshl_add_u64 v[54:55], v[54:55], 0, s[2:3]
	global_load_dword v167, v[54:55], off
	v_lshl_add_u64 v[54:55], v[54:55], 0, s[2:3]
	global_load_dword v168, v[54:55], off
	v_lshl_add_u64 v[54:55], v[54:55], 0, s[2:3]
	global_load_dword v169, v[54:55], off
	v_lshl_add_u64 v[54:55], v[54:55], 0, s[2:3]
	global_load_dword v170, v[54:55], off
	v_lshl_add_u64 v[54:55], v[54:55], 0, s[2:3]
	global_load_dword v171, v[54:55], off
	v_lshl_add_u64 v[54:55], v[54:55], 0, s[2:3]
	global_load_dword v172, v[54:55], off
	v_lshl_add_u64 v[54:55], v[54:55], 0, s[2:3]
	global_load_dword v173, v[54:55], off
	ds_read_b128 v[72:75], v0
	ds_read_b128 v[76:79], v0 offset:16
	ds_read_b128 v[80:83], v0 offset:32
	ds_read_b128 v[84:87], v0 offset:48
	ds_read_b128 v[142:145], v0 offset:64
	ds_read_b128 v[146:149], v0 offset:80
	ds_read_b128 v[150:153], v0 offset:96
	ds_read_b128 v[154:157], v0 offset:112
	s_waitcnt vmcnt(31) lgkmcnt(4)
	v_pk_fma_f32 v[56:57], v[112:113], v[72:73], v[56:57] op_sel_hi:[0,1,1]
	v_pk_fma_f32 v[58:59], v[112:113], v[74:75], v[58:59] op_sel_hi:[0,1,1]
	v_pk_fma_f32 v[60:61], v[112:113], v[76:77], v[60:61] op_sel_hi:[0,1,1]
	v_pk_fma_f32 v[62:63], v[112:113], v[78:79], v[62:63] op_sel_hi:[0,1,1]
	v_pk_fma_f32 v[66:67], v[112:113], v[80:81], v[66:67] op_sel_hi:[0,1,1]
	v_pk_fma_f32 v[68:69], v[112:113], v[82:83], v[68:69] op_sel_hi:[0,1,1]
	v_pk_fma_f32 v[70:71], v[112:113], v[84:85], v[70:71] op_sel_hi:[0,1,1]
	v_pk_fma_f32 v[64:65], v[112:113], v[86:87], v[64:65] op_sel_hi:[0,1,1]
	ds_read_b128 v[72:75], v0 offset:128
	ds_read_b128 v[76:79], v0 offset:144
	ds_read_b128 v[80:83], v0 offset:160
	ds_read_b128 v[84:87], v0 offset:176
	s_waitcnt vmcnt(30) lgkmcnt(4)
	v_pk_fma_f32 v[56:57], v[112:113], v[142:143], v[56:57] op_sel:[1,0,0] op_sel_hi:[1,1,1]
	v_pk_fma_f32 v[58:59], v[112:113], v[144:145], v[58:59] op_sel:[1,0,0] op_sel_hi:[1,1,1]
	v_pk_fma_f32 v[60:61], v[112:113], v[146:147], v[60:61] op_sel:[1,0,0] op_sel_hi:[1,1,1]
	v_pk_fma_f32 v[62:63], v[112:113], v[148:149], v[62:63] op_sel:[1,0,0] op_sel_hi:[1,1,1]
	v_pk_fma_f32 v[66:67], v[112:113], v[150:151], v[66:67] op_sel:[1,0,0] op_sel_hi:[1,1,1]
	v_pk_fma_f32 v[68:69], v[112:113], v[152:153], v[68:69] op_sel:[1,0,0] op_sel_hi:[1,1,1]
	v_pk_fma_f32 v[70:71], v[112:113], v[154:155], v[70:71] op_sel:[1,0,0] op_sel_hi:[1,1,1]
	v_pk_fma_f32 v[64:65], v[112:113], v[156:157], v[64:65] op_sel:[1,0,0] op_sel_hi:[1,1,1]
	ds_read_b128 v[142:145], v0 offset:192
	ds_read_b128 v[146:149], v0 offset:208
	ds_read_b128 v[150:153], v0 offset:224
	ds_read_b128 v[154:157], v0 offset:240
	s_waitcnt vmcnt(29) lgkmcnt(4)
	v_pk_fma_f32 v[56:57], v[114:115], v[72:73], v[56:57] op_sel_hi:[0,1,1]
	v_pk_fma_f32 v[58:59], v[114:115], v[74:75], v[58:59] op_sel_hi:[0,1,1]
	v_pk_fma_f32 v[60:61], v[114:115], v[76:77], v[60:61] op_sel_hi:[0,1,1]
	v_pk_fma_f32 v[62:63], v[114:115], v[78:79], v[62:63] op_sel_hi:[0,1,1]
	v_pk_fma_f32 v[66:67], v[114:115], v[80:81], v[66:67] op_sel_hi:[0,1,1]
	v_pk_fma_f32 v[68:69], v[114:115], v[82:83], v[68:69] op_sel_hi:[0,1,1]
	v_pk_fma_f32 v[70:71], v[114:115], v[84:85], v[70:71] op_sel_hi:[0,1,1]
	v_pk_fma_f32 v[64:65], v[114:115], v[86:87], v[64:65] op_sel_hi:[0,1,1]
	ds_read_b128 v[72:75], v0 offset:256
	ds_read_b128 v[76:79], v0 offset:272
	ds_read_b128 v[80:83], v0 offset:288
	ds_read_b128 v[84:87], v0 offset:304
	s_waitcnt vmcnt(28) lgkmcnt(4)
	v_pk_fma_f32 v[56:57], v[114:115], v[142:143], v[56:57] op_sel:[1,0,0] op_sel_hi:[1,1,1]
	v_pk_fma_f32 v[58:59], v[114:115], v[144:145], v[58:59] op_sel:[1,0,0] op_sel_hi:[1,1,1]
	v_pk_fma_f32 v[60:61], v[114:115], v[146:147], v[60:61] op_sel:[1,0,0] op_sel_hi:[1,1,1]
	v_pk_fma_f32 v[62:63], v[114:115], v[148:149], v[62:63] op_sel:[1,0,0] op_sel_hi:[1,1,1]
	v_pk_fma_f32 v[66:67], v[114:115], v[150:151], v[66:67] op_sel:[1,0,0] op_sel_hi:[1,1,1]
	v_pk_fma_f32 v[68:69], v[114:115], v[152:153], v[68:69] op_sel:[1,0,0] op_sel_hi:[1,1,1]
	v_pk_fma_f32 v[70:71], v[114:115], v[154:155], v[70:71] op_sel:[1,0,0] op_sel_hi:[1,1,1]
	v_pk_fma_f32 v[64:65], v[114:115], v[156:157], v[64:65] op_sel:[1,0,0] op_sel_hi:[1,1,1]
	ds_read_b128 v[142:145], v0 offset:320
	ds_read_b128 v[146:149], v0 offset:336
	ds_read_b128 v[150:153], v0 offset:352
	ds_read_b128 v[154:157], v0 offset:368
	s_waitcnt vmcnt(27) lgkmcnt(4)
	v_pk_fma_f32 v[56:57], v[116:117], v[72:73], v[56:57] op_sel_hi:[0,1,1]
	v_pk_fma_f32 v[58:59], v[116:117], v[74:75], v[58:59] op_sel_hi:[0,1,1]
	v_pk_fma_f32 v[60:61], v[116:117], v[76:77], v[60:61] op_sel_hi:[0,1,1]
	v_pk_fma_f32 v[62:63], v[116:117], v[78:79], v[62:63] op_sel_hi:[0,1,1]
	v_pk_fma_f32 v[66:67], v[116:117], v[80:81], v[66:67] op_sel_hi:[0,1,1]
	v_pk_fma_f32 v[68:69], v[116:117], v[82:83], v[68:69] op_sel_hi:[0,1,1]
	v_pk_fma_f32 v[70:71], v[116:117], v[84:85], v[70:71] op_sel_hi:[0,1,1]
	v_pk_fma_f32 v[64:65], v[116:117], v[86:87], v[64:65] op_sel_hi:[0,1,1]
	ds_read_b128 v[72:75], v0 offset:384
	ds_read_b128 v[76:79], v0 offset:400
	ds_read_b128 v[80:83], v0 offset:416
	ds_read_b128 v[84:87], v0 offset:432
	s_waitcnt vmcnt(26) lgkmcnt(4)
	v_pk_fma_f32 v[56:57], v[116:117], v[142:143], v[56:57] op_sel:[1,0,0] op_sel_hi:[1,1,1]
	v_pk_fma_f32 v[58:59], v[116:117], v[144:145], v[58:59] op_sel:[1,0,0] op_sel_hi:[1,1,1]
	v_pk_fma_f32 v[60:61], v[116:117], v[146:147], v[60:61] op_sel:[1,0,0] op_sel_hi:[1,1,1]
	v_pk_fma_f32 v[62:63], v[116:117], v[148:149], v[62:63] op_sel:[1,0,0] op_sel_hi:[1,1,1]
	v_pk_fma_f32 v[66:67], v[116:117], v[150:151], v[66:67] op_sel:[1,0,0] op_sel_hi:[1,1,1]
	v_pk_fma_f32 v[68:69], v[116:117], v[152:153], v[68:69] op_sel:[1,0,0] op_sel_hi:[1,1,1]
	v_pk_fma_f32 v[70:71], v[116:117], v[154:155], v[70:71] op_sel:[1,0,0] op_sel_hi:[1,1,1]
	v_pk_fma_f32 v[64:65], v[116:117], v[156:157], v[64:65] op_sel:[1,0,0] op_sel_hi:[1,1,1]
	ds_read_b128 v[142:145], v0 offset:448
	ds_read_b128 v[146:149], v0 offset:464
	ds_read_b128 v[150:153], v0 offset:480
	ds_read_b128 v[154:157], v0 offset:496
	s_waitcnt vmcnt(25) lgkmcnt(4)
	v_pk_fma_f32 v[56:57], v[118:119], v[72:73], v[56:57] op_sel_hi:[0,1,1]
	v_pk_fma_f32 v[58:59], v[118:119], v[74:75], v[58:59] op_sel_hi:[0,1,1]
	v_pk_fma_f32 v[60:61], v[118:119], v[76:77], v[60:61] op_sel_hi:[0,1,1]
	v_pk_fma_f32 v[62:63], v[118:119], v[78:79], v[62:63] op_sel_hi:[0,1,1]
	v_pk_fma_f32 v[66:67], v[118:119], v[80:81], v[66:67] op_sel_hi:[0,1,1]
	v_pk_fma_f32 v[68:69], v[118:119], v[82:83], v[68:69] op_sel_hi:[0,1,1]
	v_pk_fma_f32 v[70:71], v[118:119], v[84:85], v[70:71] op_sel_hi:[0,1,1]
	v_pk_fma_f32 v[64:65], v[118:119], v[86:87], v[64:65] op_sel_hi:[0,1,1]
	ds_read_b128 v[72:75], v0 offset:512
	ds_read_b128 v[76:79], v0 offset:528
	ds_read_b128 v[80:83], v0 offset:544
	ds_read_b128 v[84:87], v0 offset:560
	s_waitcnt vmcnt(24) lgkmcnt(4)
	v_pk_fma_f32 v[56:57], v[118:119], v[142:143], v[56:57] op_sel:[1,0,0] op_sel_hi:[1,1,1]
	v_pk_fma_f32 v[58:59], v[118:119], v[144:145], v[58:59] op_sel:[1,0,0] op_sel_hi:[1,1,1]
	v_pk_fma_f32 v[60:61], v[118:119], v[146:147], v[60:61] op_sel:[1,0,0] op_sel_hi:[1,1,1]
	v_pk_fma_f32 v[62:63], v[118:119], v[148:149], v[62:63] op_sel:[1,0,0] op_sel_hi:[1,1,1]
	v_pk_fma_f32 v[66:67], v[118:119], v[150:151], v[66:67] op_sel:[1,0,0] op_sel_hi:[1,1,1]
	v_pk_fma_f32 v[68:69], v[118:119], v[152:153], v[68:69] op_sel:[1,0,0] op_sel_hi:[1,1,1]
	v_pk_fma_f32 v[70:71], v[118:119], v[154:155], v[70:71] op_sel:[1,0,0] op_sel_hi:[1,1,1]
	v_pk_fma_f32 v[64:65], v[118:119], v[156:157], v[64:65] op_sel:[1,0,0] op_sel_hi:[1,1,1]
	ds_read_b128 v[142:145], v0 offset:576
	ds_read_b128 v[146:149], v0 offset:592
	ds_read_b128 v[150:153], v0 offset:608
	ds_read_b128 v[154:157], v0 offset:624
	s_waitcnt vmcnt(23) lgkmcnt(4)
	v_pk_fma_f32 v[56:57], v[120:121], v[72:73], v[56:57] op_sel_hi:[0,1,1]
	v_pk_fma_f32 v[58:59], v[120:121], v[74:75], v[58:59] op_sel_hi:[0,1,1]
	v_pk_fma_f32 v[60:61], v[120:121], v[76:77], v[60:61] op_sel_hi:[0,1,1]
	v_pk_fma_f32 v[62:63], v[120:121], v[78:79], v[62:63] op_sel_hi:[0,1,1]
	v_pk_fma_f32 v[66:67], v[120:121], v[80:81], v[66:67] op_sel_hi:[0,1,1]
	v_pk_fma_f32 v[68:69], v[120:121], v[82:83], v[68:69] op_sel_hi:[0,1,1]
	v_pk_fma_f32 v[70:71], v[120:121], v[84:85], v[70:71] op_sel_hi:[0,1,1]
	v_pk_fma_f32 v[64:65], v[120:121], v[86:87], v[64:65] op_sel_hi:[0,1,1]
	ds_read_b128 v[72:75], v0 offset:640
	ds_read_b128 v[76:79], v0 offset:656
	ds_read_b128 v[80:83], v0 offset:672
	ds_read_b128 v[84:87], v0 offset:688
	s_waitcnt vmcnt(22) lgkmcnt(4)
	v_pk_fma_f32 v[56:57], v[120:121], v[142:143], v[56:57] op_sel:[1,0,0] op_sel_hi:[1,1,1]
	v_pk_fma_f32 v[58:59], v[120:121], v[144:145], v[58:59] op_sel:[1,0,0] op_sel_hi:[1,1,1]
	v_pk_fma_f32 v[60:61], v[120:121], v[146:147], v[60:61] op_sel:[1,0,0] op_sel_hi:[1,1,1]
	v_pk_fma_f32 v[62:63], v[120:121], v[148:149], v[62:63] op_sel:[1,0,0] op_sel_hi:[1,1,1]
	v_pk_fma_f32 v[66:67], v[120:121], v[150:151], v[66:67] op_sel:[1,0,0] op_sel_hi:[1,1,1]
	v_pk_fma_f32 v[68:69], v[120:121], v[152:153], v[68:69] op_sel:[1,0,0] op_sel_hi:[1,1,1]
	v_pk_fma_f32 v[70:71], v[120:121], v[154:155], v[70:71] op_sel:[1,0,0] op_sel_hi:[1,1,1]
	v_pk_fma_f32 v[64:65], v[120:121], v[156:157], v[64:65] op_sel:[1,0,0] op_sel_hi:[1,1,1]
	ds_read_b128 v[142:145], v0 offset:704
	ds_read_b128 v[146:149], v0 offset:720
	ds_read_b128 v[150:153], v0 offset:736
	ds_read_b128 v[154:157], v0 offset:752
	s_waitcnt vmcnt(21) lgkmcnt(4)
	v_pk_fma_f32 v[56:57], v[122:123], v[72:73], v[56:57] op_sel_hi:[0,1,1]
	v_pk_fma_f32 v[58:59], v[122:123], v[74:75], v[58:59] op_sel_hi:[0,1,1]
	v_pk_fma_f32 v[60:61], v[122:123], v[76:77], v[60:61] op_sel_hi:[0,1,1]
	v_pk_fma_f32 v[62:63], v[122:123], v[78:79], v[62:63] op_sel_hi:[0,1,1]
	v_pk_fma_f32 v[66:67], v[122:123], v[80:81], v[66:67] op_sel_hi:[0,1,1]
	v_pk_fma_f32 v[68:69], v[122:123], v[82:83], v[68:69] op_sel_hi:[0,1,1]
	v_pk_fma_f32 v[70:71], v[122:123], v[84:85], v[70:71] op_sel_hi:[0,1,1]
	v_pk_fma_f32 v[64:65], v[122:123], v[86:87], v[64:65] op_sel_hi:[0,1,1]
	ds_read_b128 v[72:75], v0 offset:768
	ds_read_b128 v[76:79], v0 offset:784
	ds_read_b128 v[80:83], v0 offset:800
	ds_read_b128 v[84:87], v0 offset:816
	s_waitcnt vmcnt(20) lgkmcnt(4)
	v_pk_fma_f32 v[56:57], v[122:123], v[142:143], v[56:57] op_sel:[1,0,0] op_sel_hi:[1,1,1]
	v_pk_fma_f32 v[58:59], v[122:123], v[144:145], v[58:59] op_sel:[1,0,0] op_sel_hi:[1,1,1]
	v_pk_fma_f32 v[60:61], v[122:123], v[146:147], v[60:61] op_sel:[1,0,0] op_sel_hi:[1,1,1]
	v_pk_fma_f32 v[62:63], v[122:123], v[148:149], v[62:63] op_sel:[1,0,0] op_sel_hi:[1,1,1]
	v_pk_fma_f32 v[66:67], v[122:123], v[150:151], v[66:67] op_sel:[1,0,0] op_sel_hi:[1,1,1]
	v_pk_fma_f32 v[68:69], v[122:123], v[152:153], v[68:69] op_sel:[1,0,0] op_sel_hi:[1,1,1]
	v_pk_fma_f32 v[70:71], v[122:123], v[154:155], v[70:71] op_sel:[1,0,0] op_sel_hi:[1,1,1]
	v_pk_fma_f32 v[64:65], v[122:123], v[156:157], v[64:65] op_sel:[1,0,0] op_sel_hi:[1,1,1]
	ds_read_b128 v[142:145], v0 offset:832
	ds_read_b128 v[146:149], v0 offset:848
	ds_read_b128 v[150:153], v0 offset:864
	ds_read_b128 v[154:157], v0 offset:880
	s_waitcnt vmcnt(19) lgkmcnt(4)
	v_pk_fma_f32 v[56:57], v[124:125], v[72:73], v[56:57] op_sel_hi:[0,1,1]
	v_pk_fma_f32 v[58:59], v[124:125], v[74:75], v[58:59] op_sel_hi:[0,1,1]
	v_pk_fma_f32 v[60:61], v[124:125], v[76:77], v[60:61] op_sel_hi:[0,1,1]
	v_pk_fma_f32 v[62:63], v[124:125], v[78:79], v[62:63] op_sel_hi:[0,1,1]
	v_pk_fma_f32 v[66:67], v[124:125], v[80:81], v[66:67] op_sel_hi:[0,1,1]
	v_pk_fma_f32 v[68:69], v[124:125], v[82:83], v[68:69] op_sel_hi:[0,1,1]
	v_pk_fma_f32 v[70:71], v[124:125], v[84:85], v[70:71] op_sel_hi:[0,1,1]
	v_pk_fma_f32 v[64:65], v[124:125], v[86:87], v[64:65] op_sel_hi:[0,1,1]
	ds_read_b128 v[72:75], v0 offset:896
	ds_read_b128 v[76:79], v0 offset:912
	ds_read_b128 v[80:83], v0 offset:928
	ds_read_b128 v[84:87], v0 offset:944
	s_waitcnt vmcnt(18) lgkmcnt(4)
	v_pk_fma_f32 v[56:57], v[124:125], v[142:143], v[56:57] op_sel:[1,0,0] op_sel_hi:[1,1,1]
	v_pk_fma_f32 v[58:59], v[124:125], v[144:145], v[58:59] op_sel:[1,0,0] op_sel_hi:[1,1,1]
	v_pk_fma_f32 v[60:61], v[124:125], v[146:147], v[60:61] op_sel:[1,0,0] op_sel_hi:[1,1,1]
	v_pk_fma_f32 v[62:63], v[124:125], v[148:149], v[62:63] op_sel:[1,0,0] op_sel_hi:[1,1,1]
	v_pk_fma_f32 v[66:67], v[124:125], v[150:151], v[66:67] op_sel:[1,0,0] op_sel_hi:[1,1,1]
	v_pk_fma_f32 v[68:69], v[124:125], v[152:153], v[68:69] op_sel:[1,0,0] op_sel_hi:[1,1,1]
	v_pk_fma_f32 v[70:71], v[124:125], v[154:155], v[70:71] op_sel:[1,0,0] op_sel_hi:[1,1,1]
	v_pk_fma_f32 v[64:65], v[124:125], v[156:157], v[64:65] op_sel:[1,0,0] op_sel_hi:[1,1,1]
	ds_read_b128 v[142:145], v0 offset:960
	ds_read_b128 v[146:149], v0 offset:976
	ds_read_b128 v[150:153], v0 offset:992
	ds_read_b128 v[154:157], v0 offset:1008
	s_waitcnt vmcnt(17) lgkmcnt(4)
	v_pk_fma_f32 v[56:57], v[126:127], v[72:73], v[56:57] op_sel_hi:[0,1,1]
	v_pk_fma_f32 v[58:59], v[126:127], v[74:75], v[58:59] op_sel_hi:[0,1,1]
	v_pk_fma_f32 v[60:61], v[126:127], v[76:77], v[60:61] op_sel_hi:[0,1,1]
	v_pk_fma_f32 v[62:63], v[126:127], v[78:79], v[62:63] op_sel_hi:[0,1,1]
	v_pk_fma_f32 v[66:67], v[126:127], v[80:81], v[66:67] op_sel_hi:[0,1,1]
	v_pk_fma_f32 v[68:69], v[126:127], v[82:83], v[68:69] op_sel_hi:[0,1,1]
	v_pk_fma_f32 v[70:71], v[126:127], v[84:85], v[70:71] op_sel_hi:[0,1,1]
	v_pk_fma_f32 v[64:65], v[126:127], v[86:87], v[64:65] op_sel_hi:[0,1,1]
	ds_read_b128 v[72:75], v0 offset:1024
	ds_read_b128 v[76:79], v0 offset:1040
	ds_read_b128 v[80:83], v0 offset:1056
	ds_read_b128 v[84:87], v0 offset:1072
	s_waitcnt vmcnt(16) lgkmcnt(4)
	v_pk_fma_f32 v[56:57], v[126:127], v[142:143], v[56:57] op_sel:[1,0,0] op_sel_hi:[1,1,1]
	v_pk_fma_f32 v[58:59], v[126:127], v[144:145], v[58:59] op_sel:[1,0,0] op_sel_hi:[1,1,1]
	v_pk_fma_f32 v[60:61], v[126:127], v[146:147], v[60:61] op_sel:[1,0,0] op_sel_hi:[1,1,1]
	v_pk_fma_f32 v[62:63], v[126:127], v[148:149], v[62:63] op_sel:[1,0,0] op_sel_hi:[1,1,1]
	v_pk_fma_f32 v[66:67], v[126:127], v[150:151], v[66:67] op_sel:[1,0,0] op_sel_hi:[1,1,1]
	v_pk_fma_f32 v[68:69], v[126:127], v[152:153], v[68:69] op_sel:[1,0,0] op_sel_hi:[1,1,1]
	v_pk_fma_f32 v[70:71], v[126:127], v[154:155], v[70:71] op_sel:[1,0,0] op_sel_hi:[1,1,1]
	v_pk_fma_f32 v[64:65], v[126:127], v[156:157], v[64:65] op_sel:[1,0,0] op_sel_hi:[1,1,1]
	ds_read_b128 v[142:145], v0 offset:1088
	ds_read_b128 v[146:149], v0 offset:1104
	ds_read_b128 v[150:153], v0 offset:1120
	ds_read_b128 v[154:157], v0 offset:1136
	s_waitcnt vmcnt(15) lgkmcnt(4)
	v_pk_fma_f32 v[56:57], v[158:159], v[72:73], v[56:57] op_sel_hi:[0,1,1]
	v_pk_fma_f32 v[58:59], v[158:159], v[74:75], v[58:59] op_sel_hi:[0,1,1]
	v_pk_fma_f32 v[60:61], v[158:159], v[76:77], v[60:61] op_sel_hi:[0,1,1]
	v_pk_fma_f32 v[62:63], v[158:159], v[78:79], v[62:63] op_sel_hi:[0,1,1]
	v_pk_fma_f32 v[66:67], v[158:159], v[80:81], v[66:67] op_sel_hi:[0,1,1]
	v_pk_fma_f32 v[68:69], v[158:159], v[82:83], v[68:69] op_sel_hi:[0,1,1]
	v_pk_fma_f32 v[70:71], v[158:159], v[84:85], v[70:71] op_sel_hi:[0,1,1]
	v_pk_fma_f32 v[64:65], v[158:159], v[86:87], v[64:65] op_sel_hi:[0,1,1]
	ds_read_b128 v[72:75], v0 offset:1152
	ds_read_b128 v[76:79], v0 offset:1168
	ds_read_b128 v[80:83], v0 offset:1184
	ds_read_b128 v[84:87], v0 offset:1200
	s_waitcnt vmcnt(14) lgkmcnt(4)
	v_pk_fma_f32 v[56:57], v[158:159], v[142:143], v[56:57] op_sel:[1,0,0] op_sel_hi:[1,1,1]
	v_pk_fma_f32 v[58:59], v[158:159], v[144:145], v[58:59] op_sel:[1,0,0] op_sel_hi:[1,1,1]
	v_pk_fma_f32 v[60:61], v[158:159], v[146:147], v[60:61] op_sel:[1,0,0] op_sel_hi:[1,1,1]
	v_pk_fma_f32 v[62:63], v[158:159], v[148:149], v[62:63] op_sel:[1,0,0] op_sel_hi:[1,1,1]
	v_pk_fma_f32 v[66:67], v[158:159], v[150:151], v[66:67] op_sel:[1,0,0] op_sel_hi:[1,1,1]
	v_pk_fma_f32 v[68:69], v[158:159], v[152:153], v[68:69] op_sel:[1,0,0] op_sel_hi:[1,1,1]
	v_pk_fma_f32 v[70:71], v[158:159], v[154:155], v[70:71] op_sel:[1,0,0] op_sel_hi:[1,1,1]
	v_pk_fma_f32 v[64:65], v[158:159], v[156:157], v[64:65] op_sel:[1,0,0] op_sel_hi:[1,1,1]
	ds_read_b128 v[142:145], v0 offset:1216
	ds_read_b128 v[146:149], v0 offset:1232
	ds_read_b128 v[150:153], v0 offset:1248
	ds_read_b128 v[154:157], v0 offset:1264
	s_waitcnt vmcnt(13) lgkmcnt(4)
	v_pk_fma_f32 v[56:57], v[160:161], v[72:73], v[56:57] op_sel_hi:[0,1,1]
	v_pk_fma_f32 v[58:59], v[160:161], v[74:75], v[58:59] op_sel_hi:[0,1,1]
	v_pk_fma_f32 v[60:61], v[160:161], v[76:77], v[60:61] op_sel_hi:[0,1,1]
	v_pk_fma_f32 v[62:63], v[160:161], v[78:79], v[62:63] op_sel_hi:[0,1,1]
	v_pk_fma_f32 v[66:67], v[160:161], v[80:81], v[66:67] op_sel_hi:[0,1,1]
	v_pk_fma_f32 v[68:69], v[160:161], v[82:83], v[68:69] op_sel_hi:[0,1,1]
	v_pk_fma_f32 v[70:71], v[160:161], v[84:85], v[70:71] op_sel_hi:[0,1,1]
	v_pk_fma_f32 v[64:65], v[160:161], v[86:87], v[64:65] op_sel_hi:[0,1,1]
	ds_read_b128 v[72:75], v0 offset:1280
	ds_read_b128 v[76:79], v0 offset:1296
	ds_read_b128 v[80:83], v0 offset:1312
	ds_read_b128 v[84:87], v0 offset:1328
	s_waitcnt vmcnt(12) lgkmcnt(4)
	v_pk_fma_f32 v[56:57], v[160:161], v[142:143], v[56:57] op_sel:[1,0,0] op_sel_hi:[1,1,1]
	v_pk_fma_f32 v[58:59], v[160:161], v[144:145], v[58:59] op_sel:[1,0,0] op_sel_hi:[1,1,1]
	v_pk_fma_f32 v[60:61], v[160:161], v[146:147], v[60:61] op_sel:[1,0,0] op_sel_hi:[1,1,1]
	v_pk_fma_f32 v[62:63], v[160:161], v[148:149], v[62:63] op_sel:[1,0,0] op_sel_hi:[1,1,1]
	v_pk_fma_f32 v[66:67], v[160:161], v[150:151], v[66:67] op_sel:[1,0,0] op_sel_hi:[1,1,1]
	v_pk_fma_f32 v[68:69], v[160:161], v[152:153], v[68:69] op_sel:[1,0,0] op_sel_hi:[1,1,1]
	v_pk_fma_f32 v[70:71], v[160:161], v[154:155], v[70:71] op_sel:[1,0,0] op_sel_hi:[1,1,1]
	v_pk_fma_f32 v[64:65], v[160:161], v[156:157], v[64:65] op_sel:[1,0,0] op_sel_hi:[1,1,1]
	ds_read_b128 v[142:145], v0 offset:1344
	ds_read_b128 v[146:149], v0 offset:1360
	ds_read_b128 v[150:153], v0 offset:1376
	ds_read_b128 v[154:157], v0 offset:1392
	s_waitcnt vmcnt(11) lgkmcnt(4)
	v_pk_fma_f32 v[56:57], v[162:163], v[72:73], v[56:57] op_sel_hi:[0,1,1]
	v_pk_fma_f32 v[58:59], v[162:163], v[74:75], v[58:59] op_sel_hi:[0,1,1]
	v_pk_fma_f32 v[60:61], v[162:163], v[76:77], v[60:61] op_sel_hi:[0,1,1]
	v_pk_fma_f32 v[62:63], v[162:163], v[78:79], v[62:63] op_sel_hi:[0,1,1]
	v_pk_fma_f32 v[66:67], v[162:163], v[80:81], v[66:67] op_sel_hi:[0,1,1]
	v_pk_fma_f32 v[68:69], v[162:163], v[82:83], v[68:69] op_sel_hi:[0,1,1]
	v_pk_fma_f32 v[70:71], v[162:163], v[84:85], v[70:71] op_sel_hi:[0,1,1]
	v_pk_fma_f32 v[64:65], v[162:163], v[86:87], v[64:65] op_sel_hi:[0,1,1]
	ds_read_b128 v[72:75], v0 offset:1408
	ds_read_b128 v[76:79], v0 offset:1424
	ds_read_b128 v[80:83], v0 offset:1440
	ds_read_b128 v[84:87], v0 offset:1456
	s_waitcnt vmcnt(10) lgkmcnt(4)
	v_pk_fma_f32 v[56:57], v[162:163], v[142:143], v[56:57] op_sel:[1,0,0] op_sel_hi:[1,1,1]
	v_pk_fma_f32 v[58:59], v[162:163], v[144:145], v[58:59] op_sel:[1,0,0] op_sel_hi:[1,1,1]
	v_pk_fma_f32 v[60:61], v[162:163], v[146:147], v[60:61] op_sel:[1,0,0] op_sel_hi:[1,1,1]
	v_pk_fma_f32 v[62:63], v[162:163], v[148:149], v[62:63] op_sel:[1,0,0] op_sel_hi:[1,1,1]
	v_pk_fma_f32 v[66:67], v[162:163], v[150:151], v[66:67] op_sel:[1,0,0] op_sel_hi:[1,1,1]
	v_pk_fma_f32 v[68:69], v[162:163], v[152:153], v[68:69] op_sel:[1,0,0] op_sel_hi:[1,1,1]
	v_pk_fma_f32 v[70:71], v[162:163], v[154:155], v[70:71] op_sel:[1,0,0] op_sel_hi:[1,1,1]
	v_pk_fma_f32 v[64:65], v[162:163], v[156:157], v[64:65] op_sel:[1,0,0] op_sel_hi:[1,1,1]
	ds_read_b128 v[142:145], v0 offset:1472
	ds_read_b128 v[146:149], v0 offset:1488
	ds_read_b128 v[150:153], v0 offset:1504
	ds_read_b128 v[154:157], v0 offset:1520
	s_waitcnt vmcnt(9) lgkmcnt(4)
	v_pk_fma_f32 v[56:57], v[164:165], v[72:73], v[56:57] op_sel_hi:[0,1,1]
	v_pk_fma_f32 v[58:59], v[164:165], v[74:75], v[58:59] op_sel_hi:[0,1,1]
	v_pk_fma_f32 v[60:61], v[164:165], v[76:77], v[60:61] op_sel_hi:[0,1,1]
	v_pk_fma_f32 v[62:63], v[164:165], v[78:79], v[62:63] op_sel_hi:[0,1,1]
	v_pk_fma_f32 v[66:67], v[164:165], v[80:81], v[66:67] op_sel_hi:[0,1,1]
	v_pk_fma_f32 v[68:69], v[164:165], v[82:83], v[68:69] op_sel_hi:[0,1,1]
	v_pk_fma_f32 v[70:71], v[164:165], v[84:85], v[70:71] op_sel_hi:[0,1,1]
	v_pk_fma_f32 v[64:65], v[164:165], v[86:87], v[64:65] op_sel_hi:[0,1,1]
	ds_read_b128 v[72:75], v0 offset:1536
	ds_read_b128 v[76:79], v0 offset:1552
	ds_read_b128 v[80:83], v0 offset:1568
	ds_read_b128 v[84:87], v0 offset:1584
	s_waitcnt vmcnt(8) lgkmcnt(4)
	v_pk_fma_f32 v[56:57], v[164:165], v[142:143], v[56:57] op_sel:[1,0,0] op_sel_hi:[1,1,1]
	v_pk_fma_f32 v[58:59], v[164:165], v[144:145], v[58:59] op_sel:[1,0,0] op_sel_hi:[1,1,1]
	v_pk_fma_f32 v[60:61], v[164:165], v[146:147], v[60:61] op_sel:[1,0,0] op_sel_hi:[1,1,1]
	v_pk_fma_f32 v[62:63], v[164:165], v[148:149], v[62:63] op_sel:[1,0,0] op_sel_hi:[1,1,1]
	v_pk_fma_f32 v[66:67], v[164:165], v[150:151], v[66:67] op_sel:[1,0,0] op_sel_hi:[1,1,1]
	v_pk_fma_f32 v[68:69], v[164:165], v[152:153], v[68:69] op_sel:[1,0,0] op_sel_hi:[1,1,1]
	v_pk_fma_f32 v[70:71], v[164:165], v[154:155], v[70:71] op_sel:[1,0,0] op_sel_hi:[1,1,1]
	v_pk_fma_f32 v[64:65], v[164:165], v[156:157], v[64:65] op_sel:[1,0,0] op_sel_hi:[1,1,1]
	ds_read_b128 v[142:145], v0 offset:1600
	ds_read_b128 v[146:149], v0 offset:1616
	ds_read_b128 v[150:153], v0 offset:1632
	ds_read_b128 v[154:157], v0 offset:1648
	s_waitcnt vmcnt(7) lgkmcnt(4)
	v_pk_fma_f32 v[56:57], v[166:167], v[72:73], v[56:57] op_sel_hi:[0,1,1]
	v_pk_fma_f32 v[58:59], v[166:167], v[74:75], v[58:59] op_sel_hi:[0,1,1]
	v_pk_fma_f32 v[60:61], v[166:167], v[76:77], v[60:61] op_sel_hi:[0,1,1]
	v_pk_fma_f32 v[62:63], v[166:167], v[78:79], v[62:63] op_sel_hi:[0,1,1]
	v_pk_fma_f32 v[66:67], v[166:167], v[80:81], v[66:67] op_sel_hi:[0,1,1]
	v_pk_fma_f32 v[68:69], v[166:167], v[82:83], v[68:69] op_sel_hi:[0,1,1]
	v_pk_fma_f32 v[70:71], v[166:167], v[84:85], v[70:71] op_sel_hi:[0,1,1]
	v_pk_fma_f32 v[64:65], v[166:167], v[86:87], v[64:65] op_sel_hi:[0,1,1]
	ds_read_b128 v[72:75], v0 offset:1664
	ds_read_b128 v[76:79], v0 offset:1680
	ds_read_b128 v[80:83], v0 offset:1696
	ds_read_b128 v[84:87], v0 offset:1712
	s_waitcnt vmcnt(6) lgkmcnt(4)
	v_pk_fma_f32 v[56:57], v[166:167], v[142:143], v[56:57] op_sel:[1,0,0] op_sel_hi:[1,1,1]
	v_pk_fma_f32 v[58:59], v[166:167], v[144:145], v[58:59] op_sel:[1,0,0] op_sel_hi:[1,1,1]
	v_pk_fma_f32 v[60:61], v[166:167], v[146:147], v[60:61] op_sel:[1,0,0] op_sel_hi:[1,1,1]
	v_pk_fma_f32 v[62:63], v[166:167], v[148:149], v[62:63] op_sel:[1,0,0] op_sel_hi:[1,1,1]
	v_pk_fma_f32 v[66:67], v[166:167], v[150:151], v[66:67] op_sel:[1,0,0] op_sel_hi:[1,1,1]
	v_pk_fma_f32 v[68:69], v[166:167], v[152:153], v[68:69] op_sel:[1,0,0] op_sel_hi:[1,1,1]
	v_pk_fma_f32 v[70:71], v[166:167], v[154:155], v[70:71] op_sel:[1,0,0] op_sel_hi:[1,1,1]
	v_pk_fma_f32 v[64:65], v[166:167], v[156:157], v[64:65] op_sel:[1,0,0] op_sel_hi:[1,1,1]
	ds_read_b128 v[142:145], v0 offset:1728
	ds_read_b128 v[146:149], v0 offset:1744
	ds_read_b128 v[150:153], v0 offset:1760
	ds_read_b128 v[154:157], v0 offset:1776
	s_waitcnt vmcnt(5) lgkmcnt(4)
	v_pk_fma_f32 v[56:57], v[168:169], v[72:73], v[56:57] op_sel_hi:[0,1,1]
	v_pk_fma_f32 v[58:59], v[168:169], v[74:75], v[58:59] op_sel_hi:[0,1,1]
	v_pk_fma_f32 v[60:61], v[168:169], v[76:77], v[60:61] op_sel_hi:[0,1,1]
	v_pk_fma_f32 v[62:63], v[168:169], v[78:79], v[62:63] op_sel_hi:[0,1,1]
	v_pk_fma_f32 v[66:67], v[168:169], v[80:81], v[66:67] op_sel_hi:[0,1,1]
	v_pk_fma_f32 v[68:69], v[168:169], v[82:83], v[68:69] op_sel_hi:[0,1,1]
	v_pk_fma_f32 v[70:71], v[168:169], v[84:85], v[70:71] op_sel_hi:[0,1,1]
	v_pk_fma_f32 v[64:65], v[168:169], v[86:87], v[64:65] op_sel_hi:[0,1,1]
	ds_read_b128 v[72:75], v0 offset:1792
	ds_read_b128 v[76:79], v0 offset:1808
	ds_read_b128 v[80:83], v0 offset:1824
	ds_read_b128 v[84:87], v0 offset:1840
	s_waitcnt vmcnt(4) lgkmcnt(4)
	v_pk_fma_f32 v[56:57], v[168:169], v[142:143], v[56:57] op_sel:[1,0,0] op_sel_hi:[1,1,1]
	v_pk_fma_f32 v[58:59], v[168:169], v[144:145], v[58:59] op_sel:[1,0,0] op_sel_hi:[1,1,1]
	v_pk_fma_f32 v[60:61], v[168:169], v[146:147], v[60:61] op_sel:[1,0,0] op_sel_hi:[1,1,1]
	v_pk_fma_f32 v[62:63], v[168:169], v[148:149], v[62:63] op_sel:[1,0,0] op_sel_hi:[1,1,1]
	v_pk_fma_f32 v[66:67], v[168:169], v[150:151], v[66:67] op_sel:[1,0,0] op_sel_hi:[1,1,1]
	v_pk_fma_f32 v[68:69], v[168:169], v[152:153], v[68:69] op_sel:[1,0,0] op_sel_hi:[1,1,1]
	v_pk_fma_f32 v[70:71], v[168:169], v[154:155], v[70:71] op_sel:[1,0,0] op_sel_hi:[1,1,1]
	v_pk_fma_f32 v[64:65], v[168:169], v[156:157], v[64:65] op_sel:[1,0,0] op_sel_hi:[1,1,1]
	ds_read_b128 v[142:145], v0 offset:1856
	ds_read_b128 v[146:149], v0 offset:1872
	ds_read_b128 v[150:153], v0 offset:1888
	ds_read_b128 v[154:157], v0 offset:1904
	s_waitcnt vmcnt(3) lgkmcnt(4)
	v_pk_fma_f32 v[56:57], v[170:171], v[72:73], v[56:57] op_sel_hi:[0,1,1]
	v_pk_fma_f32 v[58:59], v[170:171], v[74:75], v[58:59] op_sel_hi:[0,1,1]
	v_pk_fma_f32 v[60:61], v[170:171], v[76:77], v[60:61] op_sel_hi:[0,1,1]
	v_pk_fma_f32 v[62:63], v[170:171], v[78:79], v[62:63] op_sel_hi:[0,1,1]
	v_pk_fma_f32 v[66:67], v[170:171], v[80:81], v[66:67] op_sel_hi:[0,1,1]
	v_pk_fma_f32 v[68:69], v[170:171], v[82:83], v[68:69] op_sel_hi:[0,1,1]
	v_pk_fma_f32 v[70:71], v[170:171], v[84:85], v[70:71] op_sel_hi:[0,1,1]
	v_pk_fma_f32 v[64:65], v[170:171], v[86:87], v[64:65] op_sel_hi:[0,1,1]
	ds_read_b128 v[72:75], v0 offset:1920
	ds_read_b128 v[76:79], v0 offset:1936
	ds_read_b128 v[80:83], v0 offset:1952
	ds_read_b128 v[84:87], v0 offset:1968
	s_waitcnt vmcnt(2) lgkmcnt(4)
	v_pk_fma_f32 v[56:57], v[170:171], v[142:143], v[56:57] op_sel:[1,0,0] op_sel_hi:[1,1,1]
	v_pk_fma_f32 v[58:59], v[170:171], v[144:145], v[58:59] op_sel:[1,0,0] op_sel_hi:[1,1,1]
	v_pk_fma_f32 v[60:61], v[170:171], v[146:147], v[60:61] op_sel:[1,0,0] op_sel_hi:[1,1,1]
	v_pk_fma_f32 v[62:63], v[170:171], v[148:149], v[62:63] op_sel:[1,0,0] op_sel_hi:[1,1,1]
	v_pk_fma_f32 v[66:67], v[170:171], v[150:151], v[66:67] op_sel:[1,0,0] op_sel_hi:[1,1,1]
	v_pk_fma_f32 v[68:69], v[170:171], v[152:153], v[68:69] op_sel:[1,0,0] op_sel_hi:[1,1,1]
	v_pk_fma_f32 v[70:71], v[170:171], v[154:155], v[70:71] op_sel:[1,0,0] op_sel_hi:[1,1,1]
	v_pk_fma_f32 v[64:65], v[170:171], v[156:157], v[64:65] op_sel:[1,0,0] op_sel_hi:[1,1,1]
	ds_read_b128 v[142:145], v0 offset:1984
	ds_read_b128 v[146:149], v0 offset:2000
	ds_read_b128 v[150:153], v0 offset:2016
	ds_read_b128 v[154:157], v0 offset:2032
	s_waitcnt vmcnt(1) lgkmcnt(4)
	v_pk_fma_f32 v[56:57], v[172:173], v[72:73], v[56:57] op_sel_hi:[0,1,1]
	v_pk_fma_f32 v[58:59], v[172:173], v[74:75], v[58:59] op_sel_hi:[0,1,1]
	v_pk_fma_f32 v[60:61], v[172:173], v[76:77], v[60:61] op_sel_hi:[0,1,1]
	v_pk_fma_f32 v[62:63], v[172:173], v[78:79], v[62:63] op_sel_hi:[0,1,1]
	v_pk_fma_f32 v[66:67], v[172:173], v[80:81], v[66:67] op_sel_hi:[0,1,1]
	v_pk_fma_f32 v[68:69], v[172:173], v[82:83], v[68:69] op_sel_hi:[0,1,1]
	v_pk_fma_f32 v[70:71], v[172:173], v[84:85], v[70:71] op_sel_hi:[0,1,1]
	v_pk_fma_f32 v[64:65], v[172:173], v[86:87], v[64:65] op_sel_hi:[0,1,1]
	s_waitcnt vmcnt(0) lgkmcnt(0)
	v_pk_fma_f32 v[56:57], v[172:173], v[142:143], v[56:57] op_sel:[1,0,0] op_sel_hi:[1,1,1]
	v_pk_fma_f32 v[58:59], v[172:173], v[144:145], v[58:59] op_sel:[1,0,0] op_sel_hi:[1,1,1]
	v_pk_fma_f32 v[60:61], v[172:173], v[146:147], v[60:61] op_sel:[1,0,0] op_sel_hi:[1,1,1]
	v_pk_fma_f32 v[62:63], v[172:173], v[148:149], v[62:63] op_sel:[1,0,0] op_sel_hi:[1,1,1]
	v_pk_fma_f32 v[66:67], v[172:173], v[150:151], v[66:67] op_sel:[1,0,0] op_sel_hi:[1,1,1]
	v_pk_fma_f32 v[68:69], v[172:173], v[152:153], v[68:69] op_sel:[1,0,0] op_sel_hi:[1,1,1]
	v_pk_fma_f32 v[70:71], v[172:173], v[154:155], v[70:71] op_sel:[1,0,0] op_sel_hi:[1,1,1]
	v_pk_fma_f32 v[64:65], v[172:173], v[156:157], v[64:65] op_sel:[1,0,0] op_sel_hi:[1,1,1]
	v_add_u32_e32 v0, 0x800, v0
	s_add_u32 s4, s4, 0xc0000
	s_addc_u32 s5, s5, 0
	s_cmp_eq_u32 s4, 0x600000
	s_cbranch_scc0 .LBB0_145
	v_lshl_or_b32 v52, s47, 6, v128
	v_readlane_b32 s0, v247, 13
	v_ashrrev_i32_e32 v53, 31, v52
	v_readlane_b32 s1, v247, 14
	v_readlane_b32 s6, v247, 19
	v_readlane_b32 s7, v247, 20
	s_mov_b64 s[0:1], 0
	v_mov_b32_e32 v54, v111
	v_lshl_add_u64 v[52:53], v[52:53], 2, s[6:7]
	v_mov_b32_e32 v0, v140
	v_mov_b32_e32 v19, v110
	s_barrier
	ds_write2st64_b32 v108, v56, v57 offset1:1
	ds_write2st64_b32 v108, v58, v59 offset0:2 offset1:3
	ds_write2st64_b32 v108, v60, v61 offset0:4 offset1:5
	ds_write2st64_b32 v108, v62, v63 offset0:6 offset1:7
	ds_write2st64_b32 v108, v66, v67 offset0:8 offset1:9
	ds_write2st64_b32 v108, v68, v69 offset0:10 offset1:11
	ds_write2st64_b32 v108, v70, v71 offset0:12 offset1:13
	ds_write2st64_b32 v108, v64, v65 offset0:14 offset1:15
	s_waitcnt lgkmcnt(0)
	s_barrier
	v_readlane_b32 s2, v247, 15
	v_readlane_b32 s3, v247, 16
	v_readlane_b32 s4, v247, 17
	v_readlane_b32 s5, v247, 18
	v_readlane_b32 s8, v247, 21
	v_readlane_b32 s9, v247, 22
	v_readlane_b32 s10, v247, 23
	v_readlane_b32 s11, v247, 24
	v_readlane_b32 s12, v247, 25
	v_readlane_b32 s13, v247, 26
	v_readlane_b32 s14, v247, 27
	v_readlane_b32 s15, v247, 28
